# attention A odd step: loop-carried updates (l accumulate, slot toggles, tile pointer) issued before the DMA-arrival wait and barrier
# baseline (speedup 1.0000x reference)
; __device__ __forceinline__ void finishSM(f32x16& p0, f32x16& p1, float alpha, float& l_reg, bf16x8& pa0, bf16x8& pa1, bf16x8& pa2, bf16x8& pa3) {
;     ...
;   l_reg = l_reg * alpha + ps;
; __device__ __forceinline__ void unit(const bf16* Qb, const bf16* __restrict__ Kh, const bf16* __restrict__ Vh, bf16* Ob, float lam, float post, const float* __restrict__ gsub, char* lds) {
;     ...
;   int sk = 32768, sv = 0, sw = 98304;
;     ...
;   for (int j = 1; j + 1 < NT; j += 2) {
;     A_STEP(pB0, pB1, pA0, pA1, alB, alA, j);
;     A_STEP(pA0, pA1, pB0, pB1, alA, alB, j + 1);
;   }
.LBB0_209:
	v_exp_f32_e32 v172, v128
	v_exp_f32_e32 v174, v129
	v_exp_f32_e32 v175, v130
	v_exp_f32_e32 v211, v131
	v_exp_f32_e32 v212, v132
	v_exp_f32_e32 v215, v133
	v_exp_f32_e32 v216, v134
	v_exp_f32_e32 v233, v135
	v_exp_f32_e32 v173, v136
	v_exp_f32_e32 v176, v137
	v_exp_f32_e32 v177, v138
	v_exp_f32_e32 v213, v139
	v_exp_f32_e32 v214, v140
	v_exp_f32_e32 v217, v141
	v_exp_f32_e32 v232, v142
	v_exp_f32_e32 v234, v143
	v_add_f32_e32 v115, v208, v209
	s_add_i32 s44, s44, 2
	s_xor_b32 s39, s39, 0x10000
	s_xor_b32 s56, s56, 0x10000
	v_fmac_f32_e32 v115, v207, v180
	v_add_f32_e32 v180, v113, v114
	s_add_u32 s50, s50, 0x20000
	v_fmac_f32_e32 v180, v115, v210
	s_addc_u32 s51, s51, 0
	v_mov_b32_e32 v207, v112
	s_mov_b64 s[54:55], -1
	s_and_b64 vcc, exec, s[52:53]
	s_cbranch_vccz .LBB0_211
	s_waitcnt vmcnt(0) lgkmcnt(0)
	s_mov_b64 s[54:55], 0

; __device__ __forceinline__ void unit(const bf16* Qb, const bf16* __restrict__ Kh, const bf16* __restrict__ Vh, bf16* Ob, float lam, float post, const float* __restrict__ gsub, char* lds) {
;     ...
;   for (int j = 1; j + 1 < NT; j += 2) {
;     A_STEP(pB0, pB1, pA0, pA1, alB, alA, j);
;     A_STEP(pA0, pA1, pB0, pB1, alA, alB, j + 1);
;   }
.LBB0_213:
	s_and_b64 vcc, exec, s[52:53]
	s_barrier
	s_cbranch_vccnz .LBB0_217
	s_branch .LBB0_197
